# pre-norm H stores write-through so that the SB1 leader's L2 writeback finds less dirty data
# baseline (speedup 1.0000x reference)
.LBB0_64:
	s_add_i32 s5, s10, 0xffffe000
	s_cmpk_lt_u32 s10, 0x3000
	s_cselect_b32 s16, s21, 0x3000
	s_cmpk_lt_i32 s10, 0x2000
	s_cselect_b32 s15, s11, 0
	s_cselect_b32 s14, s10, s5
	s_cselect_b32 s5, s69, s71
	s_cselect_b32 s17, s68, s70
	s_cselect_b32 s16, 0, s16
	s_lshl_b64 s[14:15], s[14:15], 12
	s_add_u32 s14, s17, s14
	s_addc_u32 s15, s5, s15
	s_lshl_b32 s5, s16, 2
	s_add_u32 s16, s19, s5
	global_load_dwordx4 v[28:31], v[8:9], off
	global_load_dwordx4 v[32:35], v[14:15], off
	global_load_dwordx4 v[36:39], v[10:11], off
	global_load_dwordx4 v[40:43], v26, s[14:15]
	global_load_dwordx4 v[44:47], v26, s[14:15] offset:1024
	global_load_dwordx4 v[48:51], v26, s[14:15] offset:3072
	global_load_dwordx4 v[52:55], v26, s[14:15] offset:2048
	s_addc_u32 s17, s20, 0
	global_load_dwordx4 v[56:59], v26, s[16:17]
	s_add_u32 s14, s16, 0x1000
	s_addc_u32 s15, s17, 0
	global_load_dwordx4 v[60:63], v26, s[14:15]
	s_add_u32 s10, s10, s6
	s_addc_u32 s11, s11, s7
	s_cmpk_lt_i32 s10, 0x4000
	s_waitcnt vmcnt(5)
	v_pk_mul_f32 v[64:65], v[42:43], v[42:43]
	v_pk_mul_f32 v[66:67], v[40:41], v[40:41]
	s_waitcnt vmcnt(4)
	v_pk_mul_f32 v[68:69], v[46:47], v[46:47]
	v_pk_mul_f32 v[70:71], v[44:45], v[44:45]
	v_pk_mov_b32 v[76:77], v[66:67], v[64:65] op_sel:[1,0]
	v_mov_b32_e32 v67, v65
	v_pk_mov_b32 v[64:65], v[70:71], v[68:69] op_sel:[1,0]
	v_mov_b32_e32 v71, v69
	s_waitcnt vmcnt(3)
	v_mul_f32_e32 v75, v48, v48
	s_waitcnt vmcnt(2)
	v_mul_f32_e32 v72, v53, v53
	v_mul_f32_e32 v74, v55, v55
	v_pk_add_f32 v[66:67], v[76:77], v[66:67]
	v_pk_add_f32 v[64:65], v[64:65], v[70:71]
	v_mul_f32_e32 v78, v49, v49
	v_mul_f32_e32 v79, v50, v50
	v_mul_f32_e32 v80, v51, v51
	v_pk_fma_f32 v[68:69], v[52:53], v[52:53], v[72:73] op_sel_hi:[1,1,0]
	v_pk_fma_f32 v[72:73], v[54:55], v[54:55], v[74:75] op_sel_hi:[1,1,0]
	s_waitcnt vmcnt(1)
	v_pk_add_f32 v[34:35], v[58:59], v[34:35]
	v_pk_add_f32 v[32:33], v[56:57], v[32:33]
	v_pk_add_f32 v[56:57], v[66:67], v[66:67] op_sel:[0,1] op_sel_hi:[1,0]
	v_pk_add_f32 v[58:59], v[64:65], v[64:65] op_sel:[0,1] op_sel_hi:[1,0]
	v_mov_b32_e32 v69, v79
	v_mov_b32_e32 v73, v80
	v_mov_b32_e32 v57, v75
	v_mov_b32_e32 v59, v78
	v_pk_add_f32 v[64:65], v[68:69], v[72:73]
	v_pk_add_f32 v[56:57], v[56:57], v[58:59]
	s_waitcnt vmcnt(0)
	v_pk_add_f32 v[36:37], v[60:61], v[36:37]
	v_pk_add_f32 v[56:57], v[56:57], v[64:65]
	v_pk_add_f32 v[38:39], v[62:63], v[38:39]
	v_add_f32_e32 v56, v56, v57
	ds_bpermute_b32 v57, v3, v56
	v_pk_add_f32 v[38:39], v[38:39], 1.0 op_sel_hi:[1,0]
	v_pk_add_f32 v[36:37], v[36:37], 1.0 op_sel_hi:[1,0]
	s_waitcnt lgkmcnt(0)
	v_add_f32_e32 v56, v56, v57
	ds_bpermute_b32 v57, v5, v56
	s_waitcnt lgkmcnt(0)
	v_add_f32_e32 v56, v56, v57
	ds_bpermute_b32 v57, v7, v56
	s_waitcnt lgkmcnt(0)
	v_add_f32_e32 v56, v56, v57
	ds_bpermute_b32 v57, v23, v56
	s_waitcnt lgkmcnt(0)
	v_add_f32_e32 v56, v56, v57
	ds_bpermute_b32 v57, v24, v56
	s_waitcnt lgkmcnt(0)
	v_add_f32_e32 v56, v56, v57
	ds_bpermute_b32 v57, v25, v56
	s_waitcnt lgkmcnt(0)
	v_add_f32_e32 v56, v56, v57
	v_fmamk_f32 v56, v56, 0x3a800000, v27
	v_mul_f32_e32 v57, 0x4b800000, v56
	v_cmp_gt_f32_e32 vcc, s22, v56
	s_nop 1
	v_cndmask_b32_e32 v56, v56, v57, vcc
	v_rsq_f32_e32 v56, v56
	s_nop 0
	v_mul_f32_e32 v57, 0x45800000, v56
	v_cndmask_b32_e32 v60, v56, v57, vcc
	v_pk_mul_f32 v[42:43], v[42:43], v[60:61] op_sel_hi:[1,0]
	v_pk_mul_f32 v[40:41], v[40:41], v[60:61] op_sel_hi:[1,0]
	v_pk_mul_f32 v[30:31], v[30:31], v[42:43]
	v_pk_mul_f32 v[28:29], v[28:29], v[40:41]
	v_pk_fma_f32 v[30:31], v[38:39], v[30:31], v[34:35]
	v_pk_fma_f32 v[28:29], v[36:37], v[28:29], v[32:33]
	v_pk_mul_f32 v[46:47], v[46:47], v[60:61] op_sel_hi:[1,0]
	v_cvt_pk_bf16_f32 v28, v28, v29
	v_cvt_pk_bf16_f32 v29, v30, v31
	global_store_dwordx2 v[20:21], v[28:29], off sc1
	global_load_dwordx4 v[28:31], v[14:15], off offset:1024
	s_nop 0
	global_load_dwordx4 v[32:35], v26, s[16:17] offset:1024
	global_load_dwordx4 v[36:39], v6, s[14:15]
	global_load_dwordx4 v[40:43], v[12:13], off
	global_load_dwordx4 v[56:59], v[8:9], off offset:1024
	v_pk_mul_f32 v[44:45], v[44:45], v[60:61] op_sel_hi:[1,0]
	v_pk_mul_f32 v[54:55], v[54:55], v[60:61] op_sel_hi:[1,0]
	v_pk_mul_f32 v[52:53], v[52:53], v[60:61] op_sel_hi:[1,0]
	v_pk_mul_f32 v[50:51], v[50:51], v[60:61] op_sel_hi:[1,0]
	v_pk_mul_f32 v[48:49], v[48:49], v[60:61] op_sel_hi:[1,0]
	s_waitcnt vmcnt(3)
	v_pk_add_f32 v[30:31], v[34:35], v[30:31]
	v_pk_add_f32 v[28:29], v[32:33], v[28:29]
	s_waitcnt vmcnt(1)
	v_pk_add_f32 v[32:33], v[38:39], v[42:43]
	v_pk_add_f32 v[34:35], v[36:37], v[40:41]
	s_waitcnt vmcnt(0)
	v_pk_mul_f32 v[36:37], v[56:57], v[44:45]
	v_pk_mul_f32 v[38:39], v[58:59], v[46:47]
	v_pk_add_f32 v[32:33], v[32:33], 1.0 op_sel_hi:[1,0]
	v_pk_add_f32 v[34:35], v[34:35], 1.0 op_sel_hi:[1,0]
	v_pk_fma_f32 v[30:31], v[32:33], v[38:39], v[30:31]
	v_pk_fma_f32 v[28:29], v[34:35], v[36:37], v[28:29]
	s_nop 0
	v_cvt_pk_bf16_f32 v28, v28, v29
	v_cvt_pk_bf16_f32 v29, v30, v31
	global_store_dwordx2 v[20:21], v[28:29], off offset:512 sc1
	global_load_dwordx4 v[28:31], v[14:15], off offset:2048
	s_nop 0
	global_load_dwordx4 v[32:35], v26, s[16:17] offset:2048
	global_load_dwordx4 v[36:39], v4, s[14:15]
	global_load_dwordx4 v[40:43], v[16:17], off
	global_load_dwordx4 v[44:47], v[8:9], off offset:2048
	s_waitcnt vmcnt(3)
	v_pk_add_f32 v[30:31], v[34:35], v[30:31]
	v_pk_add_f32 v[28:29], v[32:33], v[28:29]
	s_waitcnt vmcnt(1)
	v_pk_add_f32 v[32:33], v[38:39], v[42:43]
	v_pk_add_f32 v[34:35], v[36:37], v[40:41]
	s_waitcnt vmcnt(0)
	v_pk_mul_f32 v[36:37], v[44:45], v[52:53]
	v_pk_mul_f32 v[38:39], v[46:47], v[54:55]
	v_pk_add_f32 v[32:33], v[32:33], 1.0 op_sel_hi:[1,0]
	v_pk_add_f32 v[34:35], v[34:35], 1.0 op_sel_hi:[1,0]
	v_pk_fma_f32 v[30:31], v[38:39], v[32:33], v[30:31]
	v_pk_fma_f32 v[28:29], v[36:37], v[34:35], v[28:29]
	s_nop 0
	v_cvt_pk_bf16_f32 v28, v28, v29
	v_cvt_pk_bf16_f32 v29, v30, v31
	global_store_dwordx2 v[20:21], v[28:29], off offset:1024 sc1
	global_load_dwordx4 v[28:31], v[14:15], off offset:3072
	s_nop 0
	global_load_dwordx4 v[32:35], v26, s[16:17] offset:3072
	global_load_dwordx4 v[36:39], v2, s[14:15]
	global_load_dwordx4 v[40:43], v[18:19], off
	global_load_dwordx4 v[44:47], v[8:9], off offset:3072
	s_waitcnt vmcnt(3)
	v_pk_add_f32 v[30:31], v[34:35], v[30:31]
	v_pk_add_f32 v[28:29], v[32:33], v[28:29]
	s_waitcnt vmcnt(1)
	v_pk_add_f32 v[32:33], v[38:39], v[42:43]
	v_pk_add_f32 v[34:35], v[36:37], v[40:41]
	s_waitcnt vmcnt(0)
	v_pk_mul_f32 v[36:37], v[48:49], v[44:45]
	v_pk_mul_f32 v[38:39], v[50:51], v[46:47]
	v_pk_add_f32 v[32:33], v[32:33], 1.0 op_sel_hi:[1,0]
	v_pk_add_f32 v[34:35], v[34:35], 1.0 op_sel_hi:[1,0]
	v_pk_fma_f32 v[30:31], v[38:39], v[32:33], v[30:31]
	v_pk_fma_f32 v[28:29], v[36:37], v[34:35], v[28:29]
	s_nop 0
	v_cvt_pk_bf16_f32 v28, v28, v29
	v_cvt_pk_bf16_f32 v29, v30, v31
	global_store_dwordx2 v[20:21], v[28:29], off offset:1536 sc1
	v_lshl_add_u64 v[20:21], v[20:21], 0, s[8:9]
	s_cbranch_scc1 .LBB0_64

.LBB0_69:
	s_add_i32 s10, s4, 0xffffe000
	s_cmpk_lt_i32 s4, 0x2000
	s_cselect_b32 s11, s5, 0
	s_cselect_b32 s10, s4, s10
	s_cselect_b32 s14, s69, s71
	s_cselect_b32 s15, s68, s70
	s_lshl_b64 s[10:11], s[10:11], 12
	s_add_u32 s10, s15, s10
	s_addc_u32 s11, s14, s11
	global_load_dwordx4 v[44:47], v36, s[10:11]
	global_load_dwordx4 v[48:51], v36, s[10:11] offset:1024
	global_load_dwordx4 v[52:55], v36, s[10:11] offset:2048
	global_load_dwordx4 v[56:59], v36, s[10:11] offset:3072
	s_add_u32 s4, s4, 1
	s_addc_u32 s5, s5, 0
	s_cmp_ge_i32 s4, s8
	s_waitcnt vmcnt(3)
	v_pk_mul_f32 v[60:61], v[46:47], v[46:47]
	v_pk_mul_f32 v[62:63], v[44:45], v[44:45]
	s_waitcnt vmcnt(2)
	v_pk_mul_f32 v[64:65], v[50:51], v[50:51]
	v_pk_mul_f32 v[66:67], v[48:49], v[48:49]
	v_pk_mov_b32 v[72:73], v[62:63], v[60:61] op_sel:[1,0]
	v_mov_b32_e32 v63, v61
	v_pk_mov_b32 v[60:61], v[66:67], v[64:65] op_sel:[1,0]
	v_mov_b32_e32 v67, v65
	s_waitcnt vmcnt(0)
	v_mul_f32_e32 v71, v56, v56
	v_mul_f32_e32 v68, v53, v53
	v_mul_f32_e32 v70, v55, v55
	v_pk_add_f32 v[62:63], v[72:73], v[62:63]
	v_pk_add_f32 v[60:61], v[60:61], v[66:67]
	v_mul_f32_e32 v74, v57, v57
	v_mul_f32_e32 v75, v58, v58
	v_mul_f32_e32 v76, v59, v59
	v_pk_fma_f32 v[64:65], v[52:53], v[52:53], v[68:69] op_sel_hi:[1,1,0]
	v_pk_fma_f32 v[68:69], v[54:55], v[54:55], v[70:71] op_sel_hi:[1,1,0]
	v_pk_add_f32 v[62:63], v[62:63], v[62:63] op_sel:[0,1] op_sel_hi:[1,0]
	v_pk_add_f32 v[60:61], v[60:61], v[60:61] op_sel:[0,1] op_sel_hi:[1,0]
	v_mov_b32_e32 v65, v75
	v_mov_b32_e32 v69, v76
	v_mov_b32_e32 v63, v71
	v_mov_b32_e32 v61, v74
	v_pk_add_f32 v[64:65], v[64:65], v[68:69]
	v_pk_add_f32 v[60:61], v[62:63], v[60:61]
	s_nop 0
	v_pk_add_f32 v[60:61], v[60:61], v[64:65]
	s_nop 0
	v_add_f32_e32 v60, v60, v61
	ds_bpermute_b32 v61, v37, v60
	s_waitcnt lgkmcnt(0)
	v_add_f32_e32 v60, v60, v61
	ds_bpermute_b32 v61, v38, v60
	s_waitcnt lgkmcnt(0)
	v_add_f32_e32 v60, v60, v61
	ds_bpermute_b32 v61, v39, v60
	s_waitcnt lgkmcnt(0)
	v_add_f32_e32 v60, v60, v61
	ds_bpermute_b32 v61, v40, v60
	s_waitcnt lgkmcnt(0)
	v_add_f32_e32 v60, v60, v61
	ds_bpermute_b32 v61, v41, v60
	s_waitcnt lgkmcnt(0)
	v_add_f32_e32 v60, v60, v61
	ds_bpermute_b32 v61, v42, v60
	s_waitcnt lgkmcnt(0)
	v_add_f32_e32 v60, v60, v61
	v_fmamk_f32 v60, v60, 0x3a800000, v43
	v_mul_f32_e32 v61, 0x4b800000, v60
	v_cmp_gt_f32_e32 vcc, s9, v60
	s_nop 1
	v_cndmask_b32_e32 v60, v60, v61, vcc
	v_rsq_f32_e32 v60, v60
	s_nop 0
	v_mul_f32_e32 v61, 0x45800000, v60
	v_cndmask_b32_e32 v60, v60, v61, vcc
	v_pk_mul_f32 v[44:45], v[44:45], v[60:61] op_sel_hi:[1,0]
	v_pk_mul_f32 v[46:47], v[46:47], v[60:61] op_sel_hi:[1,0]
	v_pk_mul_f32 v[48:49], v[48:49], v[60:61] op_sel_hi:[1,0]
	v_pk_mul_f32 v[50:51], v[50:51], v[60:61] op_sel_hi:[1,0]
	v_pk_mul_f32 v[52:53], v[52:53], v[60:61] op_sel_hi:[1,0]
	v_pk_mul_f32 v[54:55], v[54:55], v[60:61] op_sel_hi:[1,0]
	v_pk_mul_f32 v[56:57], v[56:57], v[60:61] op_sel_hi:[1,0]
	v_pk_mul_f32 v[58:59], v[58:59], v[60:61] op_sel_hi:[1,0]
	v_pk_fma_f32 v[46:47], v[18:19], v[46:47], v[2:3]
	v_pk_fma_f32 v[44:45], v[20:21], v[44:45], v[4:5]
	v_pk_fma_f32 v[50:51], v[22:23], v[50:51], v[6:7]
	v_pk_fma_f32 v[48:49], v[24:25], v[48:49], v[8:9]
	v_pk_fma_f32 v[54:55], v[26:27], v[54:55], v[10:11]
	v_pk_fma_f32 v[52:53], v[28:29], v[52:53], v[12:13]
	v_pk_fma_f32 v[58:59], v[30:31], v[58:59], v[14:15]
	v_pk_fma_f32 v[56:57], v[32:33], v[56:57], v[16:17]
	v_cvt_pk_bf16_f32 v44, v44, v45
	v_cvt_pk_bf16_f32 v45, v46, v47
	v_cvt_pk_bf16_f32 v46, v48, v49
	v_cvt_pk_bf16_f32 v47, v50, v51
	v_cvt_pk_bf16_f32 v48, v52, v53
	v_cvt_pk_bf16_f32 v49, v54, v55
	v_cvt_pk_bf16_f32 v50, v56, v57
	v_cvt_pk_bf16_f32 v51, v58, v59
	global_store_dwordx2 v[34:35], v[44:45], off sc1
	global_store_dwordx2 v[34:35], v[46:47], off offset:512 sc1
	global_store_dwordx2 v[34:35], v[48:49], off offset:1024 sc1
	global_store_dwordx2 v[34:35], v[50:51], off offset:1536 sc1
	v_lshl_add_u64 v[34:35], v[34:35], 0, s[6:7]
	s_cbranch_scc0 .LBB0_69
